# init row pass: six ds_bpermute butterfly steps replaced by permlane32/16 swaps and row_shl DPP adds (lane-0 tree unchanged)
# speedup vs baseline: 1.0016x; 1.0016x over previous
.LBB0_207:
	s_waitcnt lgkmcnt(0)
	global_load_dwordx4 v[14:17], v[4:5], off offset:-3072
	global_load_dwordx4 v[18:21], v[4:5], off offset:-2048
	global_load_dwordx4 v[22:25], v[4:5], off offset:-1024
	global_load_dwordx4 v[26:29], v[4:5], off
	s_waitcnt vmcnt(0)
	v_mul_f32_e32 v30, v15, v15
	v_mul_f32_e32 v31, v19, v19
	v_mul_f32_e32 v32, v23, v23
	v_fmac_f32_e32 v30, v14, v14
	v_fmac_f32_e32 v31, v18, v18
	v_mul_f32_e32 v33, v27, v27
	v_fmac_f32_e32 v32, v22, v22
	v_fmac_f32_e32 v30, v16, v16
	v_fmac_f32_e32 v31, v20, v20
	v_fmac_f32_e32 v33, v26, v26
	v_fmac_f32_e32 v32, v24, v24
	v_fmac_f32_e32 v30, v17, v17
	v_fmac_f32_e32 v31, v21, v21
	v_fmac_f32_e32 v33, v28, v28
	v_fmac_f32_e32 v32, v25, v25
	v_add_f32_e32 v30, v30, v31
	v_fmac_f32_e32 v33, v29, v29
	v_add_f32_e32 v30, v30, v32
	v_add_f32_e32 v30, v30, v33
	v_mov_b32_e32 v100, v30
	v_mov_b32_e32 v101, v30
	v_cvt_pk_bf16_f32 v14, v14, v15
	v_cvt_pk_bf16_f32 v15, v16, v17
	v_permlane32_swap_b32_e32 v100, v101
	v_lshl_add_u64 v[30:31], s[2:3], 0, v[2:3]
	v_add_co_u32_e32 v30, vcc, s11, v30
	v_add_f32_e32 v102, v100, v101
	v_mov_b32_e32 v103, v102
	v_addc_co_u32_e32 v31, vcc, 0, v31, vcc
	global_store_dwordx2 v[30:31], v[14:15], off
	v_permlane16_swap_b32_e32 v102, v103
	v_cvt_pk_bf16_f32 v14, v18, v19
	v_cvt_pk_bf16_f32 v15, v20, v21
	v_add_f32_e32 v104, v102, v103
	global_store_dwordx2 v[30:31], v[14:15], off offset:512
	v_cvt_pk_bf16_f32 v16, v22, v23
	v_cvt_pk_bf16_f32 v17, v24, v25
	v_add_f32_dpp v105, v104, v104 row_shl:8 row_mask:0xf bank_mask:0xf
	global_store_dwordx2 v[30:31], v[16:17], off offset:1024
	v_cvt_pk_bf16_f32 v16, v26, v27
	v_cvt_pk_bf16_f32 v17, v28, v29
	v_add_f32_dpp v106, v105, v105 row_shl:4 row_mask:0xf bank_mask:0xf
	global_store_dwordx2 v[30:31], v[16:17], off offset:1536
	s_nop 1
	v_add_f32_dpp v107, v106, v106 row_shl:2 row_mask:0xf bank_mask:0xf
	s_nop 1
	v_add_f32_dpp v14, v107, v107 row_shl:1 row_mask:0xf bank_mask:0xf
	s_and_saveexec_b64 s[20:21], s[0:1]
	s_cbranch_execz .LBB0_206
	v_fmamk_f32 v14, v14, 0x3a800000, v13
	v_mul_f32_e32 v15, 0x4b800000, v14
	v_cmp_gt_f32_e32 vcc, s22, v14
	s_nop 1
	v_cndmask_b32_e32 v14, v14, v15, vcc
	v_rsq_f32_e32 v16, v14
	v_lshl_add_u64 v[14:15], s[2:3], 0, v[0:1]
	v_mul_f32_e32 v17, 0x45800000, v16
	v_cndmask_b32_e32 v16, v16, v17, vcc
	global_store_dword v[14:15], v16, off
	s_branch .LBB0_206
